# rec_pass1 constant loads hoisted above first barrier; workgroup-local barrier (own gate tiles) after the gate GEMM instead of the 4-WG panel barrier
# speedup vs baseline: 1.0219x; 1.0066x over previous
.LBB0_190:
	s_cmpk_gt_i32 s20, 0xff
	s_mov_b64 s[2:3], -1
	s_cbranch_scc0 .LBB0_292
	s_lshl_b32 s6, s20, 1
	s_cmpk_gt_u32 s20, 0x2ff
	s_cbranch_scc0 .LBB0_231
	v_mov_b32_e32 v0, v206
	s_add_i32 s2, s6, 0xfffffa00
	v_ashrrev_i32_e32 v0, 8, v0
	v_mov_b32_e32 v106, v206
	v_mov_b32_e32 v111, v206
	v_add_u32_e32 v102, s2, v0
	v_mov_b32_e32 v1, v206
	v_bfe_u32 v2, v111, 6, 2
	s_movk_i32 s2, 0x100
	v_ashrrev_i32_e32 v0, 9, v102
	v_xor_b32_e32 v3, 3, v2
	v_cmp_gt_u32_e32 vcc, s2, v1
	v_ashrrev_i32_e32 v1, 31, v0
	v_and_b32_e32 v107, 15, v111
	v_cndmask_b32_e32 v108, v3, v2, vcc
	v_lshlrev_b64 v[100:101], 13, v[0:1]
	v_lshlrev_b32_e32 v0, 6, v102
	s_movk_i32 s2, 0x1fc0
	v_lshlrev_b32_e32 v113, 4, v108
	v_and_or_b32 v12, v0, s2, v100
	v_or_b32_e32 v110, v113, v107
	v_or_b32_e32 v100, v12, v110
	v_mov_b64_e32 v[0:1], s[68:69]
	v_bfe_u32 v8, v102, 7, 2
	v_mad_u64_u32 v[0:1], s[2:3], v100, s13, v[0:1]
	v_bfe_u32 v112, v111, 4, 2
	v_mad_i32_i24 v1, v101, s13, v1
	v_lshlrev_b32_e32 v176, 6, v8
	v_lshl_add_u64 v[0:1], v[0:1], 0, v[176:177]
	v_lshlrev_b32_e32 v2, 4, v112
	v_mov_b32_e32 v3, v177
	v_lshl_add_u64 v[0:1], v[0:1], 0, v[2:3]
	s_mov_b32 s2, 0x3e80000
	v_add_co_u32_e32 v0, vcc, s2, v0
	v_mov_b32_e32 v115, v206
	s_nop 0
	v_addc_co_u32_e32 v1, vcc, 0, v1, vcc
	global_load_dwordx4 v[0:3], v[0:1], off offset:3584
	v_lshlrev_b32_e32 v104, 7, v8
	v_bfe_u32 v116, v115, 2, 6
	v_lshlrev_b32_e32 v4, 4, v115
	v_and_b32_e32 v117, 48, v4
	v_or_b32_e32 v6, v12, v116
	v_mov_b64_e32 v[4:5], s[76:77]
	v_bfe_u32 v103, v115, 5, 3
	v_mad_u64_u32 v[6:7], s[2:3], v6, s13, v[4:5]
	v_mad_i32_i24 v7, v101, s13, v7
	v_mov_b32_e32 v105, v177
	v_lshlrev_b32_e32 v114, 3, v103
	v_lshlrev_b32_e32 v109, 5, v8
	v_lshl_add_u64 v[6:7], v[6:7], 0, v[104:105]
	v_lshlrev_b32_e32 v8, 1, v117
	v_mov_b32_e32 v9, v177
	v_or_b32_e32 v167, 1, v114
	v_lshl_add_u64 v[6:7], v[6:7], 0, v[8:9]
	s_mov_b64 s[2:3], 0x1000
	v_or_b32_e32 v8, v114, v12
	v_or_b32_e32 v12, v12, v167
	v_mov_b32_e32 v13, v101
	v_lshl_add_u64 v[158:159], v[6:7], 0, s[2:3]
	v_lshlrev_b64 v[14:15], 6, v[12:13]
	v_mad_u64_u32 v[12:13], s[2:3], v12, s13, v[4:5]
	v_and_b32_e32 v166, 31, v115
	v_mov_b32_e32 v9, v101
	v_readlane_b32 s4, v254, 15
	v_mad_i32_i24 v13, v101, s13, v13
	v_lshlrev_b64 v[10:11], 6, v[8:9]
	v_readlane_b32 s5, v254, 16
	v_lshlrev_b32_e32 v40, 1, v166
	v_mov_b32_e32 v41, v177
	v_lshl_add_u64 v[12:13], v[12:13], 0, v[176:177]
	v_lshl_add_u64 v[154:155], s[4:5], 0, v[10:11]
	v_lshl_add_u64 v[14:15], s[4:5], 0, v[14:15]
	v_lshl_add_u64 v[42:43], v[12:13], 0, v[40:41]
	v_or_b32_e32 v12, 2, v8
	v_mov_b32_e32 v13, v101
	global_load_dwordx4 v[118:121], v[154:155], off offset:32
	global_load_dwordx4 v[122:125], v[154:155], off offset:16
	global_load_dwordx4 v[126:129], v[14:15], off offset:48
	global_load_dwordx4 v[130:133], v[14:15], off offset:32
	global_load_dwordx4 v[134:137], v[14:15], off offset:16
	global_load_dwordx4 v[138:141], v[14:15], off
	v_lshlrev_b64 v[14:15], 6, v[12:13]
	v_mad_u64_u32 v[12:13], s[2:3], v12, s13, v[4:5]
	v_mad_i32_i24 v13, v101, s13, v13
	v_lshl_add_u64 v[12:13], v[12:13], 0, v[176:177]
	v_lshl_add_u64 v[58:59], v[12:13], 0, v[40:41]
	v_or_b32_e32 v12, 3, v8
	v_mov_b32_e32 v13, v101
	v_lshl_add_u64 v[56:57], s[4:5], 0, v[14:15]
	v_lshlrev_b64 v[14:15], 6, v[12:13]
	v_mad_u64_u32 v[12:13], s[2:3], v12, s13, v[4:5]
	v_mad_i32_i24 v13, v101, s13, v13
	v_lshl_add_u64 v[12:13], v[12:13], 0, v[176:177]
	v_lshl_add_u64 v[14:15], s[4:5], 0, v[14:15]
	v_lshl_add_u64 v[84:85], v[12:13], 0, v[40:41]
	v_or_b32_e32 v12, 4, v8
	v_mov_b32_e32 v13, v101
	global_load_dwordx4 v[88:91], v[56:57], off offset:32
	global_load_dwordx4 v[92:95], v[56:57], off offset:16
	global_load_dwordx4 v[68:71], v[14:15], off offset:48
	global_load_dwordx4 v[72:75], v[14:15], off offset:32
	global_load_dwordx4 v[76:79], v[14:15], off offset:16
	global_load_dwordx4 v[80:83], v[14:15], off
	v_lshlrev_b64 v[14:15], 6, v[12:13]
	v_mad_u64_u32 v[12:13], s[2:3], v12, s13, v[4:5]
	v_mad_i32_i24 v13, v101, s13, v13
	v_lshl_add_u64 v[12:13], v[12:13], 0, v[176:177]
	v_lshl_add_u64 v[156:157], v[12:13], 0, v[40:41]
	v_or_b32_e32 v12, 5, v8
	v_mov_b32_e32 v13, v101
	v_lshl_add_u64 v[86:87], s[4:5], 0, v[14:15]
	v_lshlrev_b64 v[14:15], 6, v[12:13]
	v_mad_u64_u32 v[12:13], s[2:3], v12, s13, v[4:5]
	v_mad_i32_i24 v13, v101, s13, v13
	v_lshl_add_u64 v[12:13], v[12:13], 0, v[176:177]
	v_lshl_add_u64 v[14:15], s[4:5], 0, v[14:15]
	v_lshl_add_u64 v[160:161], v[12:13], 0, v[40:41]
	v_or_b32_e32 v12, 6, v8
	v_mov_b32_e32 v13, v101
	v_mad_u64_u32 v[10:11], s[2:3], v8, s13, v[4:5]
	global_load_dwordx4 v[60:63], v[86:87], off offset:32
	global_load_dwordx4 v[64:67], v[86:87], off offset:16
	global_load_dwordx4 v[36:39], v[14:15], off offset:48
	global_load_dwordx4 v[44:47], v[14:15], off offset:32
	global_load_dwordx4 v[48:51], v[14:15], off offset:16
	global_load_dwordx4 v[52:55], v[14:15], off
	v_lshlrev_b64 v[14:15], 6, v[12:13]
	v_mad_u64_u32 v[12:13], s[2:3], v12, s13, v[4:5]
	v_or_b32_e32 v8, 7, v8
	v_mad_i32_i24 v13, v101, s13, v13
	v_mad_u64_u32 v[4:5], s[2:3], v8, s13, v[4:5]
	v_mad_i32_i24 v11, v101, s13, v11
	v_lshl_add_u64 v[12:13], v[12:13], 0, v[176:177]
	v_mad_i32_i24 v5, v101, s13, v5
	s_movk_i32 s2, 0x1000
	v_lshl_add_u64 v[10:11], v[10:11], 0, v[176:177]
	v_lshl_add_u64 v[164:165], v[12:13], 0, v[40:41]
	v_lshlrev_b64 v[12:13], 6, v[8:9]
	v_lshl_add_u64 v[4:5], v[4:5], 0, v[176:177]
	v_add_co_u32_e32 v6, vcc, s2, v6
	v_lshl_add_u64 v[10:11], v[10:11], 0, v[40:41]
	v_lshl_add_u64 v[162:163], s[4:5], 0, v[14:15]
	v_lshl_add_u64 v[24:25], s[4:5], 0, v[12:13]
	v_lshl_add_u64 v[4:5], v[4:5], 0, v[40:41]
	v_addc_co_u32_e32 v7, vcc, 0, v7, vcc
	global_load_dwordx4 v[28:31], v[162:163], off offset:32
	global_load_dwordx4 v[32:35], v[162:163], off offset:16
	global_load_dwordx4 v[12:15], v[24:25], off offset:48
	global_load_dwordx4 v[16:19], v[24:25], off offset:32
	global_load_dwordx4 v[20:23], v[24:25], off offset:16
	s_nop 0
	global_load_dwordx4 v[24:27], v[24:25], off
	s_nop 0
	global_load_dwordx4 v[142:145], v[154:155], off offset:48
	global_load_ushort v168, v[10:11], off offset:3840
	global_load_dwordx4 v[146:149], v[56:57], off
	global_load_ushort v169, v[42:43], off offset:3840
	global_load_dwordx4 v[150:153], v[56:57], off offset:48
	global_load_ushort v170, v[58:59], off offset:3840
	global_load_dwordx4 v[96:99], v[86:87], off
	global_load_ushort v171, v[84:85], off offset:3840
	s_nop 0
	global_load_dwordx4 v[84:87], v[86:87], off offset:48
	s_nop 0
	global_load_ushort v172, v[156:157], off offset:3840
	global_load_dwordx4 v[56:59], v[162:163], off
	global_load_ushort v173, v[160:161], off offset:3840
	global_load_dwordx4 v[40:43], v[162:163], off offset:48
	s_nop 0
	global_load_ushort v162, v[164:165], off offset:3840
	global_load_ushort v163, v[4:5], off offset:3840
	global_load_dwordx4 v[8:11], v[6:7], off
	s_nop 0
	global_load_dwordx4 v[154:157], v[154:155], off
	s_nop 0
	global_load_dwordx4 v[4:7], v[158:159], off offset:16
	v_lshl_add_u64 v[158:159], s[82:83], 0, v[104:105]
	v_lshlrev_b32_e32 v104, 2, v166
	v_or3_b32 v160, v109, s8, v166
	v_lshl_add_u64 v[158:159], v[158:159], 0, v[104:105]
	v_ashrrev_i32_e32 v161, 31, v160
	global_load_dword v164, v[158:159], off
	global_load_dword v165, v[158:159], off offset:512
	global_load_dword v174, v[158:159], off offset:1024
	global_load_dword v175, v[158:159], off offset:1536
	global_load_dword v186, v[158:159], off offset:2048
	global_load_dword v187, v[158:159], off offset:2560
	global_load_dword v188, v[158:159], off offset:3072
	global_load_dword v189, v[158:159], off offset:3584
	v_add_co_u32_e32 v158, vcc, s2, v158
	v_lshl_add_u64 v[160:161], v[160:161], 2, s[50:51]
	s_nop 0
	v_addc_co_u32_e32 v159, vcc, 0, v159, vcc
	global_load_dword v160, v[160:161], off
	s_nop 0
	global_load_dword v161, v[158:159], off offset:512
	global_load_dword v190, v[158:159], off offset:1024
	global_load_dword v191, v[158:159], off offset:1536
	global_load_dword v192, v[158:159], off offset:2048
	global_load_dword v193, v[158:159], off offset:2560
	global_load_dword v194, v[158:159], off offset:3072
	global_load_dword v195, v[158:159], off offset:3584
	s_nop 0
	global_load_dword v158, v[158:159], off
	s_waitcnt vmcnt(0)
	s_barrier
	s_mov_b32 s3, 0xbfb8aa3b
	s_mov_b32 s2, 0x3d800000
	v_cmp_gt_u32_sdwa s[4:5], v115, v219 src0_sel:BYTE_0 src1_sel:DWORD
	s_waitcnt vmcnt(15)
	v_mul_f32_e32 v105, v155, v165
	v_fmac_f32_e32 v105, v154, v164
	s_waitcnt vmcnt(14)
	v_fmac_f32_e32 v105, v156, v174
	s_waitcnt vmcnt(13)
	v_fmac_f32_e32 v105, v157, v175
	s_waitcnt vmcnt(12)
	v_fmac_f32_e32 v105, v122, v186
	s_waitcnt vmcnt(7)
	v_mul_f32_e32 v119, v119, v161
	v_fmac_f32_e32 v105, v123, v187
	v_mul_f32_e32 v81, v81, v165
	v_fmac_f32_e32 v105, v124, v188
	v_fmac_f32_e32 v81, v80, v164
	v_mul_f32_e32 v73, v73, v161
	v_fmac_f32_e32 v105, v125, v189
	s_waitcnt vmcnt(0)
	v_fmac_f32_e32 v119, v118, v158
	v_fmac_f32_e32 v119, v120, v190
	v_fmac_f32_e32 v119, v121, v191
	v_fmac_f32_e32 v119, v142, v192
	v_fmac_f32_e32 v119, v143, v193
	v_fmac_f32_e32 v119, v144, v194
	v_fmac_f32_e32 v81, v82, v174
	v_fmac_f32_e32 v73, v72, v158
	v_mul_f32_e32 v53, v53, v165
	v_add_f32_e32 v105, v105, v160
	v_fmac_f32_e32 v119, v145, v195
	v_fmac_f32_e32 v81, v83, v175
	v_fmac_f32_e32 v73, v74, v190
	v_fmac_f32_e32 v53, v52, v164
	v_mul_f32_e32 v45, v45, v161
	v_add_f32_e32 v118, v119, v105
	v_fmac_f32_e32 v81, v76, v186
	v_fmac_f32_e32 v73, v75, v191
	v_fmac_f32_e32 v53, v54, v174
	v_fmac_f32_e32 v45, v44, v158
	v_mul_f32_e64 v105, |v118|, s3
	v_fmac_f32_e32 v81, v77, v187
	v_fmac_f32_e32 v73, v68, v192
	v_fmac_f32_e32 v53, v55, v175
	v_fmac_f32_e32 v45, v46, v190
	v_exp_f32_e32 v105, v105
	v_fmac_f32_e32 v81, v78, v188
	v_fmac_f32_e32 v73, v69, v193
	v_fmac_f32_e32 v53, v48, v186
	v_fmac_f32_e32 v45, v47, v191
	v_fmac_f32_e32 v81, v79, v189
	v_fmac_f32_e32 v73, v70, v194
	v_fmac_f32_e32 v53, v49, v187
	v_fmac_f32_e32 v45, v36, v192
	v_mul_f32_e32 v121, v139, v165
	v_add_f32_e32 v76, v81, v160
	v_fmac_f32_e32 v73, v71, v195
	v_fmac_f32_e32 v53, v50, v188
	v_fmac_f32_e32 v45, v37, v193
	v_fmac_f32_e32 v121, v138, v164
	v_mul_f32_e32 v122, v131, v161
	v_add_f32_e32 v68, v73, v76
	v_fmac_f32_e32 v53, v51, v189
	v_fmac_f32_e32 v45, v38, v194
	v_add_f32_e32 v105, 1.0, v105
	v_fmac_f32_e32 v121, v140, v174
	v_fmac_f32_e32 v122, v130, v158
	v_mul_f32_e64 v69, |v68|, s3
	v_add_f32_e32 v48, v53, v160
	v_fmac_f32_e32 v45, v39, v195
	v_log_f32_e32 v120, v105
	v_fmac_f32_e32 v121, v141, v175
	v_fmac_f32_e32 v122, v132, v190
	v_exp_f32_e32 v69, v69
	v_add_f32_e32 v36, v45, v48
	v_fmac_f32_e32 v121, v134, v186
	v_fmac_f32_e32 v122, v133, v191
	v_mul_f32_e64 v37, |v36|, s3
	v_fmac_f32_e32 v121, v135, v187
	v_fmac_f32_e32 v122, v126, v192
	v_exp_f32_e32 v37, v37
	v_min_f32_e32 v118, 0, v118
	v_fmac_f32_e32 v121, v136, v188
	v_fmac_f32_e32 v122, v127, v193
	v_fmac_f32_e32 v118, 0xbf317218, v120
	v_fmac_f32_e32 v121, v137, v189
	v_fmac_f32_e32 v122, v128, v194
	v_mul_u32_u24_e32 v123, 0x108, v103
	v_add_f32_e32 v69, 1.0, v69
	v_lshrrev_b32_e32 v119, 8, v106
	v_add_f32_e32 v121, v121, v160
	v_fmac_f32_e32 v122, v129, v195
	v_fma_f32 v118, v118, s2, 0
	v_add_lshl_u32 v123, v123, v166, 2
	s_mov_b32 s2, 0xd800
	v_log_f32_e32 v69, v69
	v_lshlrev_b32_e32 v120, 16, v168
	v_add_f32_e32 v121, v122, v121
	v_mad_i32_i24 v123, v119, s2, v123
	v_add_f32_e32 v37, 1.0, v37
	v_mul_f32_e64 v122, |v121|, s3
	ds_write2st64_b32 v123, v118, v120 offset1:68
	v_min_f32_e32 v120, 0, v121
	v_mul_f32_e32 v121, v147, v165
	v_log_f32_e32 v37, v37
	v_fmac_f32_e32 v121, v146, v164
	v_mul_f32_e32 v89, v89, v161
	v_min_f32_e32 v68, 0, v68
	v_fmac_f32_e32 v121, v148, v174
	v_fmac_f32_e32 v89, v88, v158
	v_fmac_f32_e32 v68, 0xbf317218, v69
	v_mul_f32_e32 v69, v97, v165
	v_fmac_f32_e32 v121, v149, v175
	v_fmac_f32_e32 v89, v90, v190
	v_fmac_f32_e32 v69, v96, v164
	v_mul_f32_e32 v61, v61, v161
	v_min_f32_e32 v36, 0, v36
	v_fmac_f32_e32 v121, v92, v186
	v_fmac_f32_e32 v89, v91, v191
	v_fmac_f32_e32 v69, v98, v174
	v_fmac_f32_e32 v61, v60, v158
	v_fmac_f32_e32 v36, 0xbf317218, v37
	v_mul_f32_e32 v37, v57, v165
	v_fmac_f32_e32 v121, v93, v187
	v_fmac_f32_e32 v89, v150, v192
	v_fmac_f32_e32 v69, v99, v175
	v_fmac_f32_e32 v61, v62, v190
	v_fmac_f32_e32 v37, v56, v164
	v_mul_f32_e32 v29, v29, v161
	v_mul_f32_e32 v25, v25, v165
	v_fmac_f32_e32 v121, v94, v188
	v_fmac_f32_e32 v89, v151, v193
	v_fmac_f32_e32 v69, v64, v186
	v_fmac_f32_e32 v61, v63, v191
	v_fmac_f32_e32 v37, v58, v174
	v_fmac_f32_e32 v29, v28, v158
	v_fmac_f32_e32 v25, v24, v164
	v_mul_f32_e32 v17, v17, v161
	v_fmac_f32_e32 v121, v95, v189
	v_fmac_f32_e32 v89, v152, v194
	v_fmac_f32_e32 v69, v65, v187
	v_fmac_f32_e32 v61, v84, v192
	v_fmac_f32_e32 v37, v59, v175
	v_fmac_f32_e32 v29, v30, v190
	v_fmac_f32_e32 v25, v26, v174
	v_fmac_f32_e32 v17, v16, v158
	v_add_f32_e32 v92, v121, v160
	v_fmac_f32_e32 v89, v153, v195
	v_fmac_f32_e32 v69, v66, v188
	v_fmac_f32_e32 v61, v85, v193
	v_fmac_f32_e32 v37, v32, v186
	v_fmac_f32_e32 v29, v31, v191
	v_fmac_f32_e32 v25, v27, v175
	v_fmac_f32_e32 v17, v18, v190
	v_add_f32_e32 v88, v89, v92
	v_fmac_f32_e32 v69, v67, v189
	v_fmac_f32_e32 v61, v86, v194
	v_fmac_f32_e32 v37, v33, v187
	v_fmac_f32_e32 v29, v40, v192
	v_fmac_f32_e32 v25, v20, v186
	v_fmac_f32_e32 v17, v19, v191
	v_exp_f32_e32 v122, v122
	v_mul_f32_e64 v89, |v88|, s3
	v_add_f32_e32 v64, v69, v160
	v_fmac_f32_e32 v61, v87, v195
	v_fmac_f32_e32 v37, v34, v188
	v_fmac_f32_e32 v29, v41, v193
	v_fmac_f32_e32 v25, v21, v187
	v_fmac_f32_e32 v17, v12, v192
	v_exp_f32_e32 v89, v89
	v_add_f32_e32 v60, v61, v64
	v_fmac_f32_e32 v37, v35, v189
	v_fmac_f32_e32 v29, v42, v194
	v_fmac_f32_e32 v25, v22, v188
	v_fmac_f32_e32 v17, v13, v193
	v_mul_f32_e64 v61, |v60|, s3
	v_add_f32_e32 v32, v37, v160
	v_fmac_f32_e32 v29, v43, v195
	v_fmac_f32_e32 v25, v23, v189
	v_fmac_f32_e32 v17, v14, v194
	v_exp_f32_e32 v61, v61
	v_add_f32_e32 v28, v29, v32
	v_add_f32_e32 v20, v25, v160
	v_fmac_f32_e32 v17, v15, v195
	v_add_f32_e32 v122, 1.0, v122
	v_mul_f32_e64 v29, |v28|, s3
	v_add_f32_e32 v12, v17, v20
	v_log_f32_e32 v122, v122
	v_add_f32_e32 v89, 1.0, v89
	v_exp_f32_e32 v29, v29
	v_mul_f32_e64 v13, |v12|, s3
	v_log_f32_e32 v89, v89
	v_exp_f32_e32 v13, v13
	v_add_f32_e32 v61, 1.0, v61
	v_log_f32_e32 v61, v61
	v_fmac_f32_e32 v120, 0xbf317218, v122
	v_mul_u32_u24_e32 v91, 33, v167
	v_min_f32_e32 v88, 0, v88
	v_add_f32_e32 v29, 1.0, v29
	v_fmac_f32_e32 v118, 0x3d800000, v120
	v_add_lshl_u32 v91, v91, v166, 2
	v_fmac_f32_e32 v88, 0xbf317218, v89
	v_log_f32_e32 v29, v29
	v_add_f32_e32 v13, 1.0, v13
	v_mad_i32_i24 v91, v119, s2, v91
	v_fmamk_f32 v71, v88, 0x3d800000, v118
	v_min_f32_e32 v60, 0, v60
	v_log_f32_e32 v13, v13
	ds_write2_b32 v91, v118, v71 offset1:33
	v_fmac_f32_e32 v71, 0x3d800000, v68
	v_fmac_f32_e32 v60, 0xbf317218, v61
	v_lshlrev_b32_e32 v90, 16, v169
	v_lshlrev_b32_e32 v70, 16, v170
	v_add_u32_e32 v72, 0x4400, v91
	v_fmamk_f32 v39, v60, 0x3d800000, v71
	v_min_f32_e32 v28, 0, v28
	ds_write2_b32 v72, v90, v70 offset1:33
	v_lshlrev_b32_e32 v62, 16, v171
	v_lshlrev_b32_e32 v38, 16, v172
	ds_write2_b32 v91, v71, v39 offset0:66 offset1:99
	ds_write2_b32 v72, v62, v38 offset0:66 offset1:99
	v_fmac_f32_e32 v39, 0x3d800000, v36
	v_fmac_f32_e32 v28, 0xbf317218, v29
	v_min_f32_e32 v12, 0, v12
	v_fmamk_f32 v15, v28, 0x3d800000, v39
	v_fmac_f32_e32 v12, 0xbf317218, v13
	v_mul_i32_i24_e32 v105, 0xd800, v119
	v_lshlrev_b32_e32 v30, 16, v173
	v_lshlrev_b32_e32 v14, 16, v162
	ds_write2_b32 v91, v39, v15 offset0:132 offset1:165
	ds_write2_b32 v72, v30, v14 offset0:132 offset1:165
	v_fmac_f32_e32 v15, 0x3d800000, v12
	v_lshlrev_b32_e32 v12, 8, v103
	v_or3_b32 v12, v105, v12, v104
	v_lshlrev_b32_e32 v13, 16, v163
	ds_write_b32 v91, v15 offset:792
	ds_write_b32 v91, v13 offset:18200
	ds_write_b32 v12, v15 offset:53248
	v_mul_u32_u24_e32 v12, 0x48, v117
	v_lshlrev_b32_e32 v12, 1, v12
	v_mad_i32_i24 v12, v119, s2, v12
	v_mov_b32_e32 v106, 0
	v_lshl_or_b32 v12, v116, 1, v12
	ds_write_b16 v12, v8 offset:34816
	ds_write_b16_d16_hi v12, v8 offset:34960
	ds_write_b16 v12, v9 offset:35104
	ds_write_b16_d16_hi v12, v9 offset:35248
	ds_write_b16 v12, v10 offset:35392
	ds_write_b16_d16_hi v12, v10 offset:35536
	ds_write_b16 v12, v11 offset:35680
	ds_write_b16_d16_hi v12, v11 offset:35824
	ds_write_b16 v12, v4 offset:35968
	ds_write_b16_d16_hi v12, v4 offset:36112
	ds_write_b16 v12, v5 offset:36256
	ds_write_b16_d16_hi v12, v5 offset:36400
	ds_write_b16 v12, v6 offset:36544
	ds_write_b16_d16_hi v12, v6 offset:36688
	ds_write_b16 v12, v7 offset:36832
	ds_write_b16_d16_hi v12, v7 offset:36976
	s_waitcnt lgkmcnt(0)
	s_barrier
	s_and_saveexec_b64 s[2:3], s[4:5]
	s_cbranch_execz .LBB0_196
	s_mov_b32 s4, 0xd000
	v_add3_u32 v4, v105, v104, s4
	v_mov_b32_e32 v106, 0
	s_mov_b64 s[4:5], 0

.LBB0_231:
	s_and_b64 vcc, exec, s[2:3]
	s_cbranch_vccz .LBB0_291
	v_mov_b32_e32 v0, v206
	s_addk_i32 s6, 0xfe00
	v_ashrrev_i32_e32 v0, 8, v0
	v_mov_b32_e32 v28, v206
	v_mov_b32_e32 v22, v206
	v_mov_b32_e32 v1, v206
	v_add_u32_e32 v16, s6, v0
	s_movk_i32 s2, 0x100
	v_bfe_u32 v17, v22, 6, 2
	v_ashrrev_i32_e32 v0, 9, v16
	v_cmp_gt_u32_e32 vcc, s2, v1
	v_xor_b32_e32 v1, 3, v17
	v_and_b32_e32 v26, 15, v22
	v_cndmask_b32_e32 v27, v1, v17, vcc
	v_ashrrev_i32_e32 v1, 31, v0
	v_lshlrev_b64 v[24:25], 13, v[0:1]
	v_lshlrev_b32_e32 v0, 6, v16
	s_movk_i32 s2, 0x1fc0
	v_lshlrev_b32_e32 v32, 4, v27
	v_and_or_b32 v20, v0, s2, v24
	v_or_b32_e32 v19, v32, v26
	v_or_b32_e32 v24, v20, v19
	v_mov_b64_e32 v[0:1], s[68:69]
	v_lshrrev_b32_e32 v2, 1, v16
	v_mad_u64_u32 v[0:1], s[2:3], v24, s13, v[0:1]
	v_and_b32_e32 v34, 0xc0, v2
	v_bfe_u32 v23, v22, 4, 2
	v_mad_i32_i24 v1, v25, s13, v1
	v_lshlrev_b32_e32 v176, 1, v34
	v_lshl_add_u64 v[0:1], v[0:1], 0, v[176:177]
	v_lshlrev_b32_e32 v2, 4, v23
	v_mov_b32_e32 v3, v177
	v_lshl_add_u64 v[0:1], v[0:1], 0, v[2:3]
	s_mov_b64 s[2:3], 0x3e80a00
	v_lshl_add_u64 v[2:3], v[0:1], 0, s[2:3]
	s_mov_b32 s2, 0x3e80000
	v_add_co_u32_e32 v0, vcc, s2, v0
	v_mov_b32_e32 v33, v206
	s_nop 0
	v_addc_co_u32_e32 v1, vcc, 0, v1, vcc
	global_load_dwordx4 v[4:7], v[0:1], off offset:2560
	s_nop 0
	global_load_dwordx4 v[0:3], v[2:3], off offset:64
	v_mov_b64_e32 v[36:37], s[76:77]
	v_bfe_u32 v29, v33, 6, 2
	v_bfe_u32 v30, v33, 2, 6
	v_lshlrev_b32_e32 v8, 4, v33
	v_lshlrev_b32_e32 v18, 4, v29
	v_and_b32_e32 v31, 48, v8
	v_or_b32_e32 v8, v20, v30
	v_or_b32_e32 v20, v20, v18
	v_and_b32_e32 v21, 63, v33
	v_mad_u64_u32 v[8:9], s[2:3], v8, s13, v[36:37]
	v_mad_u64_u32 v[36:37], s[2:3], v20, s13, v[36:37]
	v_mad_i32_i24 v37, v25, s13, v37
	v_lshlrev_b32_e32 v38, 1, v21
	v_mov_b32_e32 v39, v177
	v_lshl_add_u64 v[36:37], v[36:37], 0, v[38:39]
	v_mad_i32_i24 v9, v25, s13, v9
	v_lshl_add_u64 v[52:53], v[36:37], 0, v[176:177]
	s_movk_i32 s2, 0x1000
	v_lshl_add_u64 v[8:9], v[8:9], 0, v[176:177]
	v_lshlrev_b32_e32 v10, 1, v31
	v_mov_b32_e32 v11, v177
	v_add_co_u32_e32 v36, vcc, s2, v52
	v_lshl_add_u64 v[8:9], v[8:9], 0, v[10:11]
	s_nop 0
	v_addc_co_u32_e32 v37, vcc, 0, v53, vcc
	s_movk_i32 s2, 0x2000
	global_load_dwordx4 v[12:15], v[8:9], off offset:2048
	s_nop 0
	global_load_dwordx4 v[8:11], v[8:9], off offset:2064
	v_mov_b32_e32 v20, 0
	global_load_ushort v51, v[36:37], off offset:2560
	v_add_co_u32_e32 v36, vcc, s2, v52
	s_movk_i32 s2, 0x4000
	s_nop 0
	v_addc_co_u32_e32 v37, vcc, 0, v53, vcc
	global_load_ushort v50, v[36:37], off offset:3584
	v_add_co_u32_e32 v36, vcc, s2, v52
	s_movk_i32 s2, 0x5000
	s_nop 0
	v_addc_co_u32_e32 v37, vcc, 0, v53, vcc
	global_load_ushort v40, v[52:53], off offset:1536
	global_load_ushort v49, v[36:37], off offset:512
	v_add_co_u32_e32 v36, vcc, s2, v52
	s_movk_i32 s2, 0x6000
	s_nop 0
	v_addc_co_u32_e32 v37, vcc, 0, v53, vcc
	global_load_ushort v48, v[36:37], off offset:1536
	v_add_co_u32_e32 v36, vcc, s2, v52
	s_movk_i32 s2, 0x7000
	s_nop 0
	v_addc_co_u32_e32 v37, vcc, 0, v53, vcc
	global_load_ushort v47, v[36:37], off offset:2560
	v_add_co_u32_e32 v36, vcc, s2, v52
	s_mov_b32 s2, 0x9000
	s_nop 0
	v_addc_co_u32_e32 v37, vcc, 0, v53, vcc
	global_load_ushort v46, v[36:37], off offset:3584
	v_add_co_u32_e32 v36, vcc, s2, v52
	s_mov_b32 s2, 0xa000
	s_nop 0
	v_addc_co_u32_e32 v37, vcc, 0, v53, vcc
	global_load_ushort v45, v[36:37], off offset:512
	v_add_co_u32_e32 v36, vcc, s2, v52
	s_mov_b32 s2, 0xb000
	s_nop 0
	v_addc_co_u32_e32 v37, vcc, 0, v53, vcc
	global_load_ushort v44, v[36:37], off offset:1536
	v_add_co_u32_e32 v36, vcc, s2, v52
	s_mov_b32 s2, 0xc000
	s_nop 0
	v_addc_co_u32_e32 v37, vcc, 0, v53, vcc
	global_load_ushort v43, v[36:37], off offset:2560
	v_add_co_u32_e32 v36, vcc, s2, v52
	s_mov_b32 s2, 0xe000
	s_nop 0
	v_addc_co_u32_e32 v37, vcc, 0, v53, vcc
	global_load_ushort v42, v[36:37], off offset:3584
	v_add_co_u32_e32 v36, vcc, s2, v52
	s_mov_b32 s2, 0xf000
	s_nop 0
	v_addc_co_u32_e32 v37, vcc, 0, v53, vcc
	global_load_ushort v41, v[36:37], off offset:512
	v_add_co_u32_e32 v36, vcc, s2, v52
	s_mov_b32 s2, 0x10000
	s_nop 0
	v_addc_co_u32_e32 v37, vcc, 0, v53, vcc
	global_load_ushort v39, v[36:37], off offset:1536
	v_add_co_u32_e32 v36, vcc, s2, v52
	s_nop 1
	v_addc_co_u32_e32 v37, vcc, 0, v53, vcc
	global_load_ushort v38, v[36:37], off offset:2560
	v_add_co_u32_e32 v36, vcc, 0x11000, v52
	s_nop 1
	v_addc_co_u32_e32 v37, vcc, 0, v53, vcc
	v_add_co_u32_e32 v52, vcc, 0x13000, v52
	global_load_ushort v37, v[36:37], off offset:3584
	s_nop 0
	v_addc_co_u32_e32 v53, vcc, 0, v53, vcc
	global_load_ushort v35, v[52:53], off offset:512
	s_andn2_b64 vcc, exec, s[30:31]
	v_mov_b32_e32 v36, 0
	v_or_b32_e32 v62, v21, v34
	v_lshlrev_b32_e32 v62, 2, v62
	global_load_dword v63, v62, s[52:53]
	global_load_dword v64, v62, s[52:53] offset:1024
	s_waitcnt vmcnt(0)
	s_barrier
	s_cbranch_vccnz .LBB0_234
	v_mov_b32_e32 v36, v63
	v_mov_b32_e32 v34, v64
	s_mov_b32 s2, 0xf149f2ca
	v_max3_f32 v52, v36, s2, v34
	v_sub_f32_e32 v36, v36, v52
	v_sub_f32_e32 v34, v34, v52
	v_mul_f32_e32 v36, 0x3fb8aa3b, v36
	v_mul_f32_e32 v34, 0x3fb8aa3b, v34
	v_exp_f32_e32 v36, v36
	v_exp_f32_e32 v34, v34
	v_mov_b32_e32 v52, v177
	v_add_f32_e32 v53, 0, v36
	v_pk_add_f32 v[52:53], v[34:35], v[52:53] op_sel_hi:[0,1]
	v_div_scale_f32 v34, s[2:3], v53, v53, v52
	v_rcp_f32_e32 v36, v34
	v_div_scale_f32 v54, vcc, v52, v53, v52
	v_fma_f32 v55, -v34, v36, 1.0
	v_fmac_f32_e32 v36, v55, v36
	v_mul_f32_e32 v55, v54, v36
	v_fma_f32 v56, -v34, v55, v54
	v_fmac_f32_e32 v55, v56, v36
	v_fma_f32 v34, -v34, v55, v54
	v_div_fmas_f32 v34, v34, v36, v55
	v_div_fixup_f32 v36, v34, v53, v52

.Lpb_local:
	s_waitcnt vmcnt(0)
	s_barrier
	s_mov_b64 s[4:5], exec
	v_readlane_b32 s2, v254, 9
	v_readlane_b32 s3, v254, 10
	s_nop 1
	s_and_b64 s[2:3], s[4:5], s[2:3]
	s_mov_b64 exec, s[2:3]
	s_cbranch_execz .LBB0_22
	buffer_inv sc1
	s_waitcnt vmcnt(0)
	s_branch .LBB0_22
.Lpb_entry:
	s_waitcnt vmcnt(0)
	s_barrier
	s_mov_b64 s[4:5], exec
	v_readlane_b32 s2, v254, 9
	v_readlane_b32 s3, v254, 10
	s_nop 1
	s_and_b64 s[2:3], s[4:5], s[2:3]
	s_mov_b64 exec, s[2:3]
	s_cbranch_execz .LBB0_22
	buffer_inv sc1
	v_readlane_b32 s6, v254, 0
	v_readlane_b32 s8, v254, 11
	v_readlane_b32 s9, v254, 12
	s_nop 1
	s_and_b32 s7, s6, 7
	s_lshl_b32 s7, s7, 3
	s_bfe_u32 s6, s6, 0x30003
	s_add_i32 s7, s7, s6
	s_lshl_b32 s7, s7, 2
	s_addk_i32 s7, 0x300
	s_add_u32 s8, s8, s7
	s_addc_u32 s9, s9, 0
	s_mov_b32 s6, 1
	s_cmp_gt_i32 s70, 7
	s_cbranch_scc0 .Lpb_target
	s_mov_b32 s6, 2
